# the 32-column block now runs on the 128 workgroups that have no 5th in-proj GEMM unit, concurrently with the other workgroups' 5th unit
# speedup vs baseline: 1.0080x; 1.0051x over previous
; template <class Epi, class Sched>
; __device__ __forceinline__ void gemm_phase(PG8_LAS unsigned char* lds, const Gemm g, const Sched& S, const Epi& E) {
;     ...
;     for (int i = 0; i < 2; ++i) { int R, C; stage_rc(tid * 16 + i * 8192, R, C); const int Rb = Epi::PERM ? ((R & ~31) + perm32(R & 31)) : R;
;         voffA[i] = (unsigned)(R * K + C) * 2u; voffB[i] = (unsigned)(Rb * K + C) * 2u; }
;     const size_t kstep = (size_t)(BK * 2);
;     const size_t hstep = (size_t)HALF * K * 2;
;     const size_t tstep = 2 * hstep;
;     const unsigned ldsw = (unsigned)wid * 1024u;
;     const int foff = lds_byte(fr, fq * 8); const int ua = wr * 8192, ub = wc * 4096;
.LBB0_483:
	s_cmp_lt_u32 s63, 0x80
	s_cbranch_scc1 .Llg32_done
	v_readlane_b32 s47, v255, 45
	s_mul_i32 s48, s47, 0x480000
	s_add_u32 s44, s56, s48
	s_addc_u32 s45, s57, 0
	s_add_u32 s44, s44, 0x1598000
	s_addc_u32 s45, s45, 0
	v_lshrrev_b32_e32 v50, 4, v253
	v_and_b32_e32 v51, 15, v253
	v_and_b32_e32 v52, 15, v50
	v_lshrrev_b32_e32 v53, 2, v52
	v_lshlrev_b32_e32 v53, 3, v53
	v_and_b32_e32 v54, 3, v52
	v_add_u32_e32 v53, v53, v54
	v_lshrrev_b32_e32 v54, 4, v50
	v_lshl_add_u32 v53, v54, 2, v53
	v_lshlrev_b32_e32 v53, 11, v53
	v_lshl_add_u32 v53, v51, 4, v53
	v_mul_u32_u24_e32 v54, 0x820, v50
	v_lshl_add_u32 v54, v51, 4, v54
	global_load_dwordx4 v[80:83], v53, s[44:45]
	global_load_dwordx4 v[84:87], v53, s[44:45] offset:256
	global_load_dwordx4 v[88:91], v53, s[44:45] offset:512
	global_load_dwordx4 v[92:95], v53, s[44:45] offset:768
	global_load_dwordx4 v[96:99], v53, s[44:45] offset:1024
	global_load_dwordx4 v[100:103], v53, s[44:45] offset:1280
	global_load_dwordx4 v[104:107], v53, s[44:45] offset:1536
	global_load_dwordx4 v[108:111], v53, s[44:45] offset:1792
	s_waitcnt vmcnt(0)
	ds_write_b128 v54, v[80:83]
	ds_write_b128 v54, v[84:87] offset:256
	ds_write_b128 v54, v[88:91] offset:512
	ds_write_b128 v54, v[92:95] offset:768
	ds_write_b128 v54, v[96:99] offset:1024
	ds_write_b128 v54, v[100:103] offset:1280
	ds_write_b128 v54, v[104:107] offset:1536
	ds_write_b128 v54, v[108:111] offset:1792
	s_waitcnt lgkmcnt(0)
	s_barrier
	v_and_b32_e32 v55, 63, v253
	v_and_b32_e32 v56, 15, v55
	v_lshrrev_b32_e32 v57, 4, v55
	v_lshlrev_b32_e32 v50, 4, v57
	v_lshl_add_u32 v58, v56, 11, v50
	v_mul_u32_u24_e32 v61, 0x820, v56
	v_add_u32_e32 v61, v61, v50
	v_mul_u32_u24_e32 v62, 0x1200, v56
	v_add_u32_e32 v62, v62, v50
	v_add_u32_e32 v62, 0x1000, v62
	v_readfirstlane_b32 s46, v253
	s_lshr_b32 s46, s46, 6
	s_sub_i32 s47, s63, 0x80
	s_lshl_b32 s47, s47, 3
	s_add_i32 s47, s47, s46
	s_lshl_b32 s48, s47, 15
	s_mul_i32 s49, s47, 0x12000
	v_add_u32_e32 v60, s48, v58
	v_add_u32_e32 v63, s49, v62
	global_load_dwordx4 v[80:83], v60, s[66:67]
	global_load_dwordx4 v[84:87], v60, s[66:67] offset:64
	global_load_dwordx4 v[88:91], v60, s[66:67] offset:128
	global_load_dwordx4 v[92:95], v60, s[66:67] offset:192
	global_load_dwordx4 v[96:99], v60, s[66:67] offset:256
	global_load_dwordx4 v[100:103], v60, s[66:67] offset:320
	global_load_dwordx4 v[104:107], v60, s[66:67] offset:384
	global_load_dwordx4 v[108:111], v60, s[66:67] offset:448
	global_load_dwordx4 v[112:115], v60, s[66:67] offset:512
	global_load_dwordx4 v[116:119], v60, s[66:67] offset:576
	global_load_dwordx4 v[120:123], v60, s[66:67] offset:640
	global_load_dwordx4 v[124:127], v60, s[66:67] offset:704
	global_load_dwordx4 v[128:131], v60, s[66:67] offset:768
	global_load_dwordx4 v[132:135], v60, s[66:67] offset:832
	global_load_dwordx4 v[136:139], v60, s[66:67] offset:896
	global_load_dwordx4 v[140:143], v60, s[66:67] offset:960
	global_load_dwordx4 v[144:147], v60, s[66:67] offset:1024
	global_load_dwordx4 v[148:151], v60, s[66:67] offset:1088
	global_load_dwordx4 v[156:159], v60, s[66:67] offset:1152
	global_load_dwordx4 v[160:163], v60, s[66:67] offset:1216
	global_load_dwordx4 v[164:167], v60, s[66:67] offset:1280
	global_load_dwordx4 v[168:171], v60, s[66:67] offset:1344
	global_load_dwordx4 v[172:175], v60, s[66:67] offset:1408
	global_load_dwordx4 v[176:179], v60, s[66:67] offset:1472
	global_load_dwordx4 v[180:183], v60, s[66:67] offset:1536
	global_load_dwordx4 v[184:187], v60, s[66:67] offset:1600
	global_load_dwordx4 v[188:191], v60, s[66:67] offset:1664
	global_load_dwordx4 v[192:195], v60, s[66:67] offset:1728
	global_load_dwordx4 v[196:199], v60, s[66:67] offset:1792
	global_load_dwordx4 v[200:203], v60, s[66:67] offset:1856
	global_load_dwordx4 v[204:207], v60, s[66:67] offset:1920
	global_load_dwordx4 v[224:227], v60, s[66:67] offset:1984
	v_mov_b32_e32 v42, 0
	v_mov_b32_e32 v43, 0
	v_mov_b32_e32 v44, 0
	v_mov_b32_e32 v45, 0
	v_mov_b32_e32 v46, 0
	v_mov_b32_e32 v47, 0
	v_mov_b32_e32 v48, 0
	v_mov_b32_e32 v49, 0
	ds_read_b128 v[228:231], v61 offset:0
	ds_read_b128 v[232:235], v61 offset:33280
	ds_read_b128 v[236:239], v61 offset:64
	ds_read_b128 v[240:243], v61 offset:33344
	ds_read_b128 v[244:247], v61 offset:128
	ds_read_b128 v[248:251], v61 offset:33408
	ds_read_b128 v[34:37], v61 offset:192
	ds_read_b128 v[38:41], v61 offset:33472
	s_waitcnt vmcnt(31)
	s_waitcnt lgkmcnt(6)
	v_mfma_f32_16x16x32_bf16 v[42:45], v[228:231], v[80:83], v[42:45]
	v_mfma_f32_16x16x32_bf16 v[46:49], v[232:235], v[80:83], v[46:49]
	ds_read_b128 v[228:231], v61 offset:256
	ds_read_b128 v[232:235], v61 offset:33536
	s_waitcnt vmcnt(30)
	s_waitcnt lgkmcnt(6)
	v_mfma_f32_16x16x32_bf16 v[42:45], v[236:239], v[84:87], v[42:45]
	v_mfma_f32_16x16x32_bf16 v[46:49], v[240:243], v[84:87], v[46:49]
	ds_read_b128 v[236:239], v61 offset:320
	ds_read_b128 v[240:243], v61 offset:33600
	s_waitcnt vmcnt(29)
	s_waitcnt lgkmcnt(6)
	v_mfma_f32_16x16x32_bf16 v[42:45], v[244:247], v[88:91], v[42:45]
	v_mfma_f32_16x16x32_bf16 v[46:49], v[248:251], v[88:91], v[46:49]
	ds_read_b128 v[244:247], v61 offset:384
	ds_read_b128 v[248:251], v61 offset:33664
	s_waitcnt vmcnt(28)
	s_waitcnt lgkmcnt(6)
	v_mfma_f32_16x16x32_bf16 v[42:45], v[34:37], v[92:95], v[42:45]
	v_mfma_f32_16x16x32_bf16 v[46:49], v[38:41], v[92:95], v[46:49]
	ds_read_b128 v[34:37], v61 offset:448
	ds_read_b128 v[38:41], v61 offset:33728
	s_waitcnt vmcnt(27)
	s_waitcnt lgkmcnt(6)
	v_mfma_f32_16x16x32_bf16 v[42:45], v[228:231], v[96:99], v[42:45]
	v_mfma_f32_16x16x32_bf16 v[46:49], v[232:235], v[96:99], v[46:49]
	ds_read_b128 v[228:231], v61 offset:512
	ds_read_b128 v[232:235], v61 offset:33792
	s_waitcnt vmcnt(26)
	s_waitcnt lgkmcnt(6)
	v_mfma_f32_16x16x32_bf16 v[42:45], v[236:239], v[100:103], v[42:45]
	v_mfma_f32_16x16x32_bf16 v[46:49], v[240:243], v[100:103], v[46:49]
	ds_read_b128 v[236:239], v61 offset:576
	ds_read_b128 v[240:243], v61 offset:33856
	s_waitcnt vmcnt(25)
	s_waitcnt lgkmcnt(6)
	v_mfma_f32_16x16x32_bf16 v[42:45], v[244:247], v[104:107], v[42:45]
	v_mfma_f32_16x16x32_bf16 v[46:49], v[248:251], v[104:107], v[46:49]
	ds_read_b128 v[244:247], v61 offset:640
	ds_read_b128 v[248:251], v61 offset:33920
	s_waitcnt vmcnt(24)
	s_waitcnt lgkmcnt(6)
	v_mfma_f32_16x16x32_bf16 v[42:45], v[34:37], v[108:111], v[42:45]
	v_mfma_f32_16x16x32_bf16 v[46:49], v[38:41], v[108:111], v[46:49]
	ds_read_b128 v[34:37], v61 offset:704
	ds_read_b128 v[38:41], v61 offset:33984
	s_waitcnt vmcnt(23)
	s_waitcnt lgkmcnt(6)
	v_mfma_f32_16x16x32_bf16 v[42:45], v[228:231], v[112:115], v[42:45]
	v_mfma_f32_16x16x32_bf16 v[46:49], v[232:235], v[112:115], v[46:49]
	ds_read_b128 v[228:231], v61 offset:768
	ds_read_b128 v[232:235], v61 offset:34048
	s_waitcnt vmcnt(22)
	s_waitcnt lgkmcnt(6)
	v_mfma_f32_16x16x32_bf16 v[42:45], v[236:239], v[116:119], v[42:45]
	v_mfma_f32_16x16x32_bf16 v[46:49], v[240:243], v[116:119], v[46:49]
	ds_read_b128 v[236:239], v61 offset:832
	ds_read_b128 v[240:243], v61 offset:34112
	s_waitcnt vmcnt(21)
	s_waitcnt lgkmcnt(6)
	v_mfma_f32_16x16x32_bf16 v[42:45], v[244:247], v[120:123], v[42:45]
	v_mfma_f32_16x16x32_bf16 v[46:49], v[248:251], v[120:123], v[46:49]
	ds_read_b128 v[244:247], v61 offset:896
	ds_read_b128 v[248:251], v61 offset:34176
	s_waitcnt vmcnt(20)
	s_waitcnt lgkmcnt(6)
	v_mfma_f32_16x16x32_bf16 v[42:45], v[34:37], v[124:127], v[42:45]
	v_mfma_f32_16x16x32_bf16 v[46:49], v[38:41], v[124:127], v[46:49]
	ds_read_b128 v[34:37], v61 offset:960
	ds_read_b128 v[38:41], v61 offset:34240
	s_waitcnt vmcnt(19)
	s_waitcnt lgkmcnt(6)
	v_mfma_f32_16x16x32_bf16 v[42:45], v[228:231], v[128:131], v[42:45]
	v_mfma_f32_16x16x32_bf16 v[46:49], v[232:235], v[128:131], v[46:49]
	ds_read_b128 v[228:231], v61 offset:1024
	ds_read_b128 v[232:235], v61 offset:34304
	s_waitcnt vmcnt(18)
	s_waitcnt lgkmcnt(6)
	v_mfma_f32_16x16x32_bf16 v[42:45], v[236:239], v[132:135], v[42:45]
	v_mfma_f32_16x16x32_bf16 v[46:49], v[240:243], v[132:135], v[46:49]
	ds_read_b128 v[236:239], v61 offset:1088
	ds_read_b128 v[240:243], v61 offset:34368
	s_waitcnt vmcnt(17)
	s_waitcnt lgkmcnt(6)
	v_mfma_f32_16x16x32_bf16 v[42:45], v[244:247], v[136:139], v[42:45]
	v_mfma_f32_16x16x32_bf16 v[46:49], v[248:251], v[136:139], v[46:49]
	ds_read_b128 v[244:247], v61 offset:1152
	ds_read_b128 v[248:251], v61 offset:34432
	s_waitcnt vmcnt(16)
	s_waitcnt lgkmcnt(6)
	v_mfma_f32_16x16x32_bf16 v[42:45], v[34:37], v[140:143], v[42:45]
	v_mfma_f32_16x16x32_bf16 v[46:49], v[38:41], v[140:143], v[46:49]
	ds_read_b128 v[34:37], v61 offset:1216
	ds_read_b128 v[38:41], v61 offset:34496
	s_waitcnt vmcnt(15)
	s_waitcnt lgkmcnt(6)
	v_mfma_f32_16x16x32_bf16 v[42:45], v[228:231], v[144:147], v[42:45]
	v_mfma_f32_16x16x32_bf16 v[46:49], v[232:235], v[144:147], v[46:49]
	ds_read_b128 v[228:231], v61 offset:1280
	ds_read_b128 v[232:235], v61 offset:34560
	s_waitcnt vmcnt(14)
	s_waitcnt lgkmcnt(6)
	v_mfma_f32_16x16x32_bf16 v[42:45], v[236:239], v[148:151], v[42:45]
	v_mfma_f32_16x16x32_bf16 v[46:49], v[240:243], v[148:151], v[46:49]
	ds_read_b128 v[236:239], v61 offset:1344
	ds_read_b128 v[240:243], v61 offset:34624
	s_waitcnt vmcnt(13)
	s_waitcnt lgkmcnt(6)
	v_mfma_f32_16x16x32_bf16 v[42:45], v[244:247], v[156:159], v[42:45]
	v_mfma_f32_16x16x32_bf16 v[46:49], v[248:251], v[156:159], v[46:49]
	ds_read_b128 v[244:247], v61 offset:1408
	ds_read_b128 v[248:251], v61 offset:34688
	s_waitcnt vmcnt(12)
	s_waitcnt lgkmcnt(6)
	v_mfma_f32_16x16x32_bf16 v[42:45], v[34:37], v[160:163], v[42:45]
	v_mfma_f32_16x16x32_bf16 v[46:49], v[38:41], v[160:163], v[46:49]
	ds_read_b128 v[34:37], v61 offset:1472
	ds_read_b128 v[38:41], v61 offset:34752
	s_waitcnt vmcnt(11)
	s_waitcnt lgkmcnt(6)
	v_mfma_f32_16x16x32_bf16 v[42:45], v[228:231], v[164:167], v[42:45]
	v_mfma_f32_16x16x32_bf16 v[46:49], v[232:235], v[164:167], v[46:49]
	ds_read_b128 v[228:231], v61 offset:1536
	ds_read_b128 v[232:235], v61 offset:34816
	s_waitcnt vmcnt(10)
	s_waitcnt lgkmcnt(6)
	v_mfma_f32_16x16x32_bf16 v[42:45], v[236:239], v[168:171], v[42:45]
	v_mfma_f32_16x16x32_bf16 v[46:49], v[240:243], v[168:171], v[46:49]
	ds_read_b128 v[236:239], v61 offset:1600
	ds_read_b128 v[240:243], v61 offset:34880
	s_waitcnt vmcnt(9)
	s_waitcnt lgkmcnt(6)
	v_mfma_f32_16x16x32_bf16 v[42:45], v[244:247], v[172:175], v[42:45]
	v_mfma_f32_16x16x32_bf16 v[46:49], v[248:251], v[172:175], v[46:49]
	ds_read_b128 v[244:247], v61 offset:1664
	ds_read_b128 v[248:251], v61 offset:34944
	s_waitcnt vmcnt(8)
	s_waitcnt lgkmcnt(6)
	v_mfma_f32_16x16x32_bf16 v[42:45], v[34:37], v[176:179], v[42:45]
	v_mfma_f32_16x16x32_bf16 v[46:49], v[38:41], v[176:179], v[46:49]
	ds_read_b128 v[34:37], v61 offset:1728
	ds_read_b128 v[38:41], v61 offset:35008
	s_waitcnt vmcnt(7)
	s_waitcnt lgkmcnt(6)
	v_mfma_f32_16x16x32_bf16 v[42:45], v[228:231], v[180:183], v[42:45]
	v_mfma_f32_16x16x32_bf16 v[46:49], v[232:235], v[180:183], v[46:49]
	ds_read_b128 v[228:231], v61 offset:1792
	ds_read_b128 v[232:235], v61 offset:35072
	s_waitcnt vmcnt(6)
	s_waitcnt lgkmcnt(6)
	v_mfma_f32_16x16x32_bf16 v[42:45], v[236:239], v[184:187], v[42:45]
	v_mfma_f32_16x16x32_bf16 v[46:49], v[240:243], v[184:187], v[46:49]
	ds_read_b128 v[236:239], v61 offset:1856
	ds_read_b128 v[240:243], v61 offset:35136
	s_waitcnt vmcnt(5)
	s_waitcnt lgkmcnt(6)
; __device__ __forceinline__ unsigned cvt_pk_bf16(float lo, float hi) { const f32x2c f = {lo, hi}; return __builtin_bit_cast(unsigned, __builtin_convertvector(f, bf16x2c)); }
;     __device__ __forceinline__ void operator()(const f32x4 (&acc)[2][2][4][2], const Unit& u, int wr, int wc, int fr, int fq) const {
;     ...
;                 for (int bj = 0; bj < 2; ++bj) { const f32x4 v0 = acc[ai][bj][m][0], v1 = acc[ai][bj][m][1];
;                     u32x4 w; w.x = cvt_pk_bf16(v0[0], v0[1]); w.y = cvt_pk_bf16(v0[2], v0[3]); w.z = cvt_pk_bf16(v1[0], v1[1]); w.w = cvt_pk_bf16(v1[2], v1[3]);
;                     *(u32x4*)(rowp + bj * HALF) = w; } }
	v_mfma_f32_16x16x32_bf16 v[42:45], v[244:247], v[188:191], v[42:45]
	v_mfma_f32_16x16x32_bf16 v[46:49], v[248:251], v[188:191], v[46:49]
	ds_read_b128 v[244:247], v61 offset:1920
	ds_read_b128 v[248:251], v61 offset:35200
	s_waitcnt vmcnt(4)
	s_waitcnt lgkmcnt(6)
	v_mfma_f32_16x16x32_bf16 v[42:45], v[34:37], v[192:195], v[42:45]
	v_mfma_f32_16x16x32_bf16 v[46:49], v[38:41], v[192:195], v[46:49]
	ds_read_b128 v[34:37], v61 offset:1984
	ds_read_b128 v[38:41], v61 offset:35264
	s_waitcnt vmcnt(3)
	s_waitcnt lgkmcnt(6)
	v_mfma_f32_16x16x32_bf16 v[42:45], v[228:231], v[196:199], v[42:45]
	v_mfma_f32_16x16x32_bf16 v[46:49], v[232:235], v[196:199], v[46:49]
	s_waitcnt vmcnt(2)
	s_waitcnt lgkmcnt(4)
	v_mfma_f32_16x16x32_bf16 v[42:45], v[236:239], v[200:203], v[42:45]
	v_mfma_f32_16x16x32_bf16 v[46:49], v[240:243], v[200:203], v[46:49]
	s_waitcnt vmcnt(1)
	s_waitcnt lgkmcnt(2)
	v_mfma_f32_16x16x32_bf16 v[42:45], v[244:247], v[204:207], v[42:45]
	v_mfma_f32_16x16x32_bf16 v[46:49], v[248:251], v[204:207], v[46:49]
	s_waitcnt vmcnt(0)
	s_waitcnt lgkmcnt(0)
	v_mfma_f32_16x16x32_bf16 v[42:45], v[34:37], v[224:227], v[42:45]
	v_mfma_f32_16x16x32_bf16 v[46:49], v[38:41], v[224:227], v[46:49]
	s_nop 7
	s_nop 1
	v_cvt_pk_bf16_f32 v64, v42, v43
	v_cvt_pk_bf16_f32 v65, v44, v45
	v_cvt_pk_bf16_f32 v66, v46, v47
	v_cvt_pk_bf16_f32 v67, v48, v49
	global_store_dwordx4 v63, v[64:67], s[68:69]
	s_addk_i32 s47, 0x400
	s_lshl_b32 s48, s47, 15
	s_mul_i32 s49, s47, 0x12000
	v_add_u32_e32 v60, s48, v58
	v_add_u32_e32 v63, s49, v62
	global_load_dwordx4 v[80:83], v60, s[66:67]
	global_load_dwordx4 v[84:87], v60, s[66:67] offset:64
	global_load_dwordx4 v[88:91], v60, s[66:67] offset:128
	global_load_dwordx4 v[92:95], v60, s[66:67] offset:192
	global_load_dwordx4 v[96:99], v60, s[66:67] offset:256
	global_load_dwordx4 v[100:103], v60, s[66:67] offset:320
	global_load_dwordx4 v[104:107], v60, s[66:67] offset:384
	global_load_dwordx4 v[108:111], v60, s[66:67] offset:448
	global_load_dwordx4 v[112:115], v60, s[66:67] offset:512
	global_load_dwordx4 v[116:119], v60, s[66:67] offset:576
	global_load_dwordx4 v[120:123], v60, s[66:67] offset:640
	global_load_dwordx4 v[124:127], v60, s[66:67] offset:704
	global_load_dwordx4 v[128:131], v60, s[66:67] offset:768
	global_load_dwordx4 v[132:135], v60, s[66:67] offset:832
	global_load_dwordx4 v[136:139], v60, s[66:67] offset:896
	global_load_dwordx4 v[140:143], v60, s[66:67] offset:960
	global_load_dwordx4 v[144:147], v60, s[66:67] offset:1024
	global_load_dwordx4 v[148:151], v60, s[66:67] offset:1088
	global_load_dwordx4 v[156:159], v60, s[66:67] offset:1152
	global_load_dwordx4 v[160:163], v60, s[66:67] offset:1216
	global_load_dwordx4 v[164:167], v60, s[66:67] offset:1280
	global_load_dwordx4 v[168:171], v60, s[66:67] offset:1344
	global_load_dwordx4 v[172:175], v60, s[66:67] offset:1408
	global_load_dwordx4 v[176:179], v60, s[66:67] offset:1472
	global_load_dwordx4 v[180:183], v60, s[66:67] offset:1536
	global_load_dwordx4 v[184:187], v60, s[66:67] offset:1600
	global_load_dwordx4 v[188:191], v60, s[66:67] offset:1664
	global_load_dwordx4 v[192:195], v60, s[66:67] offset:1728
	global_load_dwordx4 v[196:199], v60, s[66:67] offset:1792
	global_load_dwordx4 v[200:203], v60, s[66:67] offset:1856
	global_load_dwordx4 v[204:207], v60, s[66:67] offset:1920
	global_load_dwordx4 v[224:227], v60, s[66:67] offset:1984
	v_mov_b32_e32 v42, 0
	v_mov_b32_e32 v43, 0
	v_mov_b32_e32 v44, 0
	v_mov_b32_e32 v45, 0
	v_mov_b32_e32 v46, 0
	v_mov_b32_e32 v47, 0
	v_mov_b32_e32 v48, 0
	v_mov_b32_e32 v49, 0
	ds_read_b128 v[228:231], v61 offset:0
	ds_read_b128 v[232:235], v61 offset:33280
	ds_read_b128 v[236:239], v61 offset:64
	ds_read_b128 v[240:243], v61 offset:33344
	ds_read_b128 v[244:247], v61 offset:128
	ds_read_b128 v[248:251], v61 offset:33408
	ds_read_b128 v[34:37], v61 offset:192
	ds_read_b128 v[38:41], v61 offset:33472
	s_waitcnt vmcnt(31)
	s_waitcnt lgkmcnt(6)
	v_mfma_f32_16x16x32_bf16 v[42:45], v[228:231], v[80:83], v[42:45]
	v_mfma_f32_16x16x32_bf16 v[46:49], v[232:235], v[80:83], v[46:49]
	ds_read_b128 v[228:231], v61 offset:256
	ds_read_b128 v[232:235], v61 offset:33536
	s_waitcnt vmcnt(30)
	s_waitcnt lgkmcnt(6)
	v_mfma_f32_16x16x32_bf16 v[42:45], v[236:239], v[84:87], v[42:45]
	v_mfma_f32_16x16x32_bf16 v[46:49], v[240:243], v[84:87], v[46:49]
	ds_read_b128 v[236:239], v61 offset:320
	ds_read_b128 v[240:243], v61 offset:33600
	s_waitcnt vmcnt(29)
	s_waitcnt lgkmcnt(6)
	v_mfma_f32_16x16x32_bf16 v[42:45], v[244:247], v[88:91], v[42:45]
	v_mfma_f32_16x16x32_bf16 v[46:49], v[248:251], v[88:91], v[46:49]
	ds_read_b128 v[244:247], v61 offset:384
	ds_read_b128 v[248:251], v61 offset:33664
	s_waitcnt vmcnt(28)
	s_waitcnt lgkmcnt(6)
	v_mfma_f32_16x16x32_bf16 v[42:45], v[34:37], v[92:95], v[42:45]
	v_mfma_f32_16x16x32_bf16 v[46:49], v[38:41], v[92:95], v[46:49]
	ds_read_b128 v[34:37], v61 offset:448
	ds_read_b128 v[38:41], v61 offset:33728
	s_waitcnt vmcnt(27)
	s_waitcnt lgkmcnt(6)
	v_mfma_f32_16x16x32_bf16 v[42:45], v[228:231], v[96:99], v[42:45]
	v_mfma_f32_16x16x32_bf16 v[46:49], v[232:235], v[96:99], v[46:49]
	ds_read_b128 v[228:231], v61 offset:512
	ds_read_b128 v[232:235], v61 offset:33792
	s_waitcnt vmcnt(26)
	s_waitcnt lgkmcnt(6)
	v_mfma_f32_16x16x32_bf16 v[42:45], v[236:239], v[100:103], v[42:45]
	v_mfma_f32_16x16x32_bf16 v[46:49], v[240:243], v[100:103], v[46:49]
	ds_read_b128 v[236:239], v61 offset:576
	ds_read_b128 v[240:243], v61 offset:33856
	s_waitcnt vmcnt(25)
	s_waitcnt lgkmcnt(6)
	v_mfma_f32_16x16x32_bf16 v[42:45], v[244:247], v[104:107], v[42:45]
	v_mfma_f32_16x16x32_bf16 v[46:49], v[248:251], v[104:107], v[46:49]
	ds_read_b128 v[244:247], v61 offset:640
	ds_read_b128 v[248:251], v61 offset:33920
	s_waitcnt vmcnt(24)
; __device__ __forceinline__ unsigned cvt_pk_bf16(float lo, float hi) { const f32x2c f = {lo, hi}; return __builtin_bit_cast(unsigned, __builtin_convertvector(f, bf16x2c)); }
;     __device__ __forceinline__ void operator()(const f32x4 (&acc)[2][2][4][2], const Unit& u, int wr, int wc, int fr, int fq) const {
;     ...
;                 for (int bj = 0; bj < 2; ++bj) { const f32x4 v0 = acc[ai][bj][m][0], v1 = acc[ai][bj][m][1];
;                     u32x4 w; w.x = cvt_pk_bf16(v0[0], v0[1]); w.y = cvt_pk_bf16(v0[2], v0[3]); w.z = cvt_pk_bf16(v1[0], v1[1]); w.w = cvt_pk_bf16(v1[2], v1[3]);
;                     *(u32x4*)(rowp + bj * HALF) = w; } }
	s_waitcnt lgkmcnt(6)
	v_mfma_f32_16x16x32_bf16 v[42:45], v[34:37], v[108:111], v[42:45]
	v_mfma_f32_16x16x32_bf16 v[46:49], v[38:41], v[108:111], v[46:49]
	ds_read_b128 v[34:37], v61 offset:704
	ds_read_b128 v[38:41], v61 offset:33984
	s_waitcnt vmcnt(23)
	s_waitcnt lgkmcnt(6)
	v_mfma_f32_16x16x32_bf16 v[42:45], v[228:231], v[112:115], v[42:45]
	v_mfma_f32_16x16x32_bf16 v[46:49], v[232:235], v[112:115], v[46:49]
	ds_read_b128 v[228:231], v61 offset:768
	ds_read_b128 v[232:235], v61 offset:34048
	s_waitcnt vmcnt(22)
	s_waitcnt lgkmcnt(6)
	v_mfma_f32_16x16x32_bf16 v[42:45], v[236:239], v[116:119], v[42:45]
	v_mfma_f32_16x16x32_bf16 v[46:49], v[240:243], v[116:119], v[46:49]
	ds_read_b128 v[236:239], v61 offset:832
	ds_read_b128 v[240:243], v61 offset:34112
	s_waitcnt vmcnt(21)
	s_waitcnt lgkmcnt(6)
	v_mfma_f32_16x16x32_bf16 v[42:45], v[244:247], v[120:123], v[42:45]
	v_mfma_f32_16x16x32_bf16 v[46:49], v[248:251], v[120:123], v[46:49]
	ds_read_b128 v[244:247], v61 offset:896
	ds_read_b128 v[248:251], v61 offset:34176
	s_waitcnt vmcnt(20)
	s_waitcnt lgkmcnt(6)
	v_mfma_f32_16x16x32_bf16 v[42:45], v[34:37], v[124:127], v[42:45]
	v_mfma_f32_16x16x32_bf16 v[46:49], v[38:41], v[124:127], v[46:49]
	ds_read_b128 v[34:37], v61 offset:960
	ds_read_b128 v[38:41], v61 offset:34240
	s_waitcnt vmcnt(19)
	s_waitcnt lgkmcnt(6)
	v_mfma_f32_16x16x32_bf16 v[42:45], v[228:231], v[128:131], v[42:45]
	v_mfma_f32_16x16x32_bf16 v[46:49], v[232:235], v[128:131], v[46:49]
	ds_read_b128 v[228:231], v61 offset:1024
	ds_read_b128 v[232:235], v61 offset:34304
	s_waitcnt vmcnt(18)
	s_waitcnt lgkmcnt(6)
	v_mfma_f32_16x16x32_bf16 v[42:45], v[236:239], v[132:135], v[42:45]
	v_mfma_f32_16x16x32_bf16 v[46:49], v[240:243], v[132:135], v[46:49]
	ds_read_b128 v[236:239], v61 offset:1088
	ds_read_b128 v[240:243], v61 offset:34368
	s_waitcnt vmcnt(17)
	s_waitcnt lgkmcnt(6)
	v_mfma_f32_16x16x32_bf16 v[42:45], v[244:247], v[136:139], v[42:45]
	v_mfma_f32_16x16x32_bf16 v[46:49], v[248:251], v[136:139], v[46:49]
	ds_read_b128 v[244:247], v61 offset:1152
	ds_read_b128 v[248:251], v61 offset:34432
	s_waitcnt vmcnt(16)
	s_waitcnt lgkmcnt(6)
	v_mfma_f32_16x16x32_bf16 v[42:45], v[34:37], v[140:143], v[42:45]
	v_mfma_f32_16x16x32_bf16 v[46:49], v[38:41], v[140:143], v[46:49]
	ds_read_b128 v[34:37], v61 offset:1216
	ds_read_b128 v[38:41], v61 offset:34496
	s_waitcnt vmcnt(15)
	s_waitcnt lgkmcnt(6)
	v_mfma_f32_16x16x32_bf16 v[42:45], v[228:231], v[144:147], v[42:45]
	v_mfma_f32_16x16x32_bf16 v[46:49], v[232:235], v[144:147], v[46:49]
	ds_read_b128 v[228:231], v61 offset:1280
	ds_read_b128 v[232:235], v61 offset:34560
	s_waitcnt vmcnt(14)
	s_waitcnt lgkmcnt(6)
	v_mfma_f32_16x16x32_bf16 v[42:45], v[236:239], v[148:151], v[42:45]
	v_mfma_f32_16x16x32_bf16 v[46:49], v[240:243], v[148:151], v[46:49]
	ds_read_b128 v[236:239], v61 offset:1344
	ds_read_b128 v[240:243], v61 offset:34624
	s_waitcnt vmcnt(13)
	s_waitcnt lgkmcnt(6)
	v_mfma_f32_16x16x32_bf16 v[42:45], v[244:247], v[156:159], v[42:45]
	v_mfma_f32_16x16x32_bf16 v[46:49], v[248:251], v[156:159], v[46:49]
	ds_read_b128 v[244:247], v61 offset:1408
	ds_read_b128 v[248:251], v61 offset:34688
	s_waitcnt vmcnt(12)
	s_waitcnt lgkmcnt(6)
	v_mfma_f32_16x16x32_bf16 v[42:45], v[34:37], v[160:163], v[42:45]
	v_mfma_f32_16x16x32_bf16 v[46:49], v[38:41], v[160:163], v[46:49]
	ds_read_b128 v[34:37], v61 offset:1472
	ds_read_b128 v[38:41], v61 offset:34752
	s_waitcnt vmcnt(11)
	s_waitcnt lgkmcnt(6)
	v_mfma_f32_16x16x32_bf16 v[42:45], v[228:231], v[164:167], v[42:45]
	v_mfma_f32_16x16x32_bf16 v[46:49], v[232:235], v[164:167], v[46:49]
	ds_read_b128 v[228:231], v61 offset:1536
	ds_read_b128 v[232:235], v61 offset:34816
	s_waitcnt vmcnt(10)
	s_waitcnt lgkmcnt(6)
	v_mfma_f32_16x16x32_bf16 v[42:45], v[236:239], v[168:171], v[42:45]
	v_mfma_f32_16x16x32_bf16 v[46:49], v[240:243], v[168:171], v[46:49]
	ds_read_b128 v[236:239], v61 offset:1600
	ds_read_b128 v[240:243], v61 offset:34880
	s_waitcnt vmcnt(9)
	s_waitcnt lgkmcnt(6)
	v_mfma_f32_16x16x32_bf16 v[42:45], v[244:247], v[172:175], v[42:45]
	v_mfma_f32_16x16x32_bf16 v[46:49], v[248:251], v[172:175], v[46:49]
	ds_read_b128 v[244:247], v61 offset:1664
	ds_read_b128 v[248:251], v61 offset:34944
	s_waitcnt vmcnt(8)
	s_waitcnt lgkmcnt(6)
	v_mfma_f32_16x16x32_bf16 v[42:45], v[34:37], v[176:179], v[42:45]
	v_mfma_f32_16x16x32_bf16 v[46:49], v[38:41], v[176:179], v[46:49]
	ds_read_b128 v[34:37], v61 offset:1728
	ds_read_b128 v[38:41], v61 offset:35008
	s_waitcnt vmcnt(7)
	s_waitcnt lgkmcnt(6)
	v_mfma_f32_16x16x32_bf16 v[42:45], v[228:231], v[180:183], v[42:45]
	v_mfma_f32_16x16x32_bf16 v[46:49], v[232:235], v[180:183], v[46:49]
	ds_read_b128 v[228:231], v61 offset:1792
	ds_read_b128 v[232:235], v61 offset:35072
	s_waitcnt vmcnt(6)
	s_waitcnt lgkmcnt(6)
	v_mfma_f32_16x16x32_bf16 v[42:45], v[236:239], v[184:187], v[42:45]
	v_mfma_f32_16x16x32_bf16 v[46:49], v[240:243], v[184:187], v[46:49]
	ds_read_b128 v[236:239], v61 offset:1856
	ds_read_b128 v[240:243], v61 offset:35136
	s_waitcnt vmcnt(5)
	s_waitcnt lgkmcnt(6)
	v_mfma_f32_16x16x32_bf16 v[42:45], v[244:247], v[188:191], v[42:45]
	v_mfma_f32_16x16x32_bf16 v[46:49], v[248:251], v[188:191], v[46:49]
	ds_read_b128 v[244:247], v61 offset:1920
	ds_read_b128 v[248:251], v61 offset:35200
	s_waitcnt vmcnt(4)
	s_waitcnt lgkmcnt(6)
	v_mfma_f32_16x16x32_bf16 v[42:45], v[34:37], v[192:195], v[42:45]
	v_mfma_f32_16x16x32_bf16 v[46:49], v[38:41], v[192:195], v[46:49]
	ds_read_b128 v[34:37], v61 offset:1984
	ds_read_b128 v[38:41], v61 offset:35264
	s_waitcnt vmcnt(3)
	s_waitcnt lgkmcnt(6)
	v_mfma_f32_16x16x32_bf16 v[42:45], v[228:231], v[196:199], v[42:45]
	v_mfma_f32_16x16x32_bf16 v[46:49], v[232:235], v[196:199], v[46:49]
	s_waitcnt vmcnt(2)
	s_waitcnt lgkmcnt(4)
	v_mfma_f32_16x16x32_bf16 v[42:45], v[236:239], v[200:203], v[42:45]
	v_mfma_f32_16x16x32_bf16 v[46:49], v[240:243], v[200:203], v[46:49]
	s_waitcnt vmcnt(1)
	s_waitcnt lgkmcnt(2)
	v_mfma_f32_16x16x32_bf16 v[42:45], v[244:247], v[204:207], v[42:45]
	v_mfma_f32_16x16x32_bf16 v[46:49], v[248:251], v[204:207], v[46:49]
	s_waitcnt vmcnt(0)
	s_waitcnt lgkmcnt(0)
	v_mfma_f32_16x16x32_bf16 v[42:45], v[34:37], v[224:227], v[42:45]
	v_mfma_f32_16x16x32_bf16 v[46:49], v[38:41], v[224:227], v[46:49]
	s_nop 7
	s_nop 1
	v_cvt_pk_bf16_f32 v64, v42, v43
	v_cvt_pk_bf16_f32 v65, v44, v45
	v_cvt_pk_bf16_f32 v66, v46, v47
	v_cvt_pk_bf16_f32 v67, v48, v49
	global_store_dwordx4 v63, v[64:67], s[68:69]
	s_cmp_gt_u32 s46, 1
	s_cbranch_scc1 .Llg32_done
; __device__ __forceinline__ unsigned cvt_pk_bf16(float lo, float hi) { const f32x2c f = {lo, hi}; return __builtin_bit_cast(unsigned, __builtin_convertvector(f, bf16x2c)); }
;     __device__ __forceinline__ void operator()(const f32x4 (&acc)[2][2][4][2], const Unit& u, int wr, int wc, int fr, int fq) const {
;     ...
;                 for (int bj = 0; bj < 2; ++bj) { const f32x4 v0 = acc[ai][bj][m][0], v1 = acc[ai][bj][m][1];
;                     u32x4 w; w.x = cvt_pk_bf16(v0[0], v0[1]); w.y = cvt_pk_bf16(v0[2], v0[3]); w.z = cvt_pk_bf16(v1[0], v1[1]); w.w = cvt_pk_bf16(v1[2], v1[3]);
;                     *(u32x4*)(rowp + bj * HALF) = w; } }
	s_sub_i32 s47, s63, 0x80
	s_lshl_b32 s47, s47, 1
	s_add_i32 s47, s47, s46
	s_addk_i32 s47, 0x800
	s_lshl_b32 s48, s47, 15
	s_mul_i32 s49, s47, 0x12000
	v_add_u32_e32 v60, s48, v58
	v_add_u32_e32 v63, s49, v62
	global_load_dwordx4 v[80:83], v60, s[66:67]
	global_load_dwordx4 v[84:87], v60, s[66:67] offset:64
	global_load_dwordx4 v[88:91], v60, s[66:67] offset:128
	global_load_dwordx4 v[92:95], v60, s[66:67] offset:192
	global_load_dwordx4 v[96:99], v60, s[66:67] offset:256
	global_load_dwordx4 v[100:103], v60, s[66:67] offset:320
	global_load_dwordx4 v[104:107], v60, s[66:67] offset:384
	global_load_dwordx4 v[108:111], v60, s[66:67] offset:448
	global_load_dwordx4 v[112:115], v60, s[66:67] offset:512
	global_load_dwordx4 v[116:119], v60, s[66:67] offset:576
	global_load_dwordx4 v[120:123], v60, s[66:67] offset:640
	global_load_dwordx4 v[124:127], v60, s[66:67] offset:704
	global_load_dwordx4 v[128:131], v60, s[66:67] offset:768
	global_load_dwordx4 v[132:135], v60, s[66:67] offset:832
	global_load_dwordx4 v[136:139], v60, s[66:67] offset:896
	global_load_dwordx4 v[140:143], v60, s[66:67] offset:960
	global_load_dwordx4 v[144:147], v60, s[66:67] offset:1024
	global_load_dwordx4 v[148:151], v60, s[66:67] offset:1088
	global_load_dwordx4 v[156:159], v60, s[66:67] offset:1152
	global_load_dwordx4 v[160:163], v60, s[66:67] offset:1216
	global_load_dwordx4 v[164:167], v60, s[66:67] offset:1280
	global_load_dwordx4 v[168:171], v60, s[66:67] offset:1344
	global_load_dwordx4 v[172:175], v60, s[66:67] offset:1408
	global_load_dwordx4 v[176:179], v60, s[66:67] offset:1472
	global_load_dwordx4 v[180:183], v60, s[66:67] offset:1536
	global_load_dwordx4 v[184:187], v60, s[66:67] offset:1600
	global_load_dwordx4 v[188:191], v60, s[66:67] offset:1664
	global_load_dwordx4 v[192:195], v60, s[66:67] offset:1728
	global_load_dwordx4 v[196:199], v60, s[66:67] offset:1792
	global_load_dwordx4 v[200:203], v60, s[66:67] offset:1856
	global_load_dwordx4 v[204:207], v60, s[66:67] offset:1920
	global_load_dwordx4 v[224:227], v60, s[66:67] offset:1984
	v_mov_b32_e32 v42, 0
	v_mov_b32_e32 v43, 0
	v_mov_b32_e32 v44, 0
	v_mov_b32_e32 v45, 0
	v_mov_b32_e32 v46, 0
	v_mov_b32_e32 v47, 0
	v_mov_b32_e32 v48, 0
	v_mov_b32_e32 v49, 0
	ds_read_b128 v[228:231], v61 offset:0
	ds_read_b128 v[232:235], v61 offset:33280
	ds_read_b128 v[236:239], v61 offset:64
	ds_read_b128 v[240:243], v61 offset:33344
	ds_read_b128 v[244:247], v61 offset:128
	ds_read_b128 v[248:251], v61 offset:33408
	ds_read_b128 v[34:37], v61 offset:192
	ds_read_b128 v[38:41], v61 offset:33472
	s_waitcnt vmcnt(31)
	s_waitcnt lgkmcnt(6)
	v_mfma_f32_16x16x32_bf16 v[42:45], v[228:231], v[80:83], v[42:45]
	v_mfma_f32_16x16x32_bf16 v[46:49], v[232:235], v[80:83], v[46:49]
	ds_read_b128 v[228:231], v61 offset:256
	ds_read_b128 v[232:235], v61 offset:33536
	s_waitcnt vmcnt(30)
	s_waitcnt lgkmcnt(6)
	v_mfma_f32_16x16x32_bf16 v[42:45], v[236:239], v[84:87], v[42:45]
	v_mfma_f32_16x16x32_bf16 v[46:49], v[240:243], v[84:87], v[46:49]
	ds_read_b128 v[236:239], v61 offset:320
	ds_read_b128 v[240:243], v61 offset:33600
	s_waitcnt vmcnt(29)
	s_waitcnt lgkmcnt(6)
	v_mfma_f32_16x16x32_bf16 v[42:45], v[244:247], v[88:91], v[42:45]
	v_mfma_f32_16x16x32_bf16 v[46:49], v[248:251], v[88:91], v[46:49]
	ds_read_b128 v[244:247], v61 offset:384
	ds_read_b128 v[248:251], v61 offset:33664
	s_waitcnt vmcnt(28)
	s_waitcnt lgkmcnt(6)
	v_mfma_f32_16x16x32_bf16 v[42:45], v[34:37], v[92:95], v[42:45]
	v_mfma_f32_16x16x32_bf16 v[46:49], v[38:41], v[92:95], v[46:49]
	ds_read_b128 v[34:37], v61 offset:448
	ds_read_b128 v[38:41], v61 offset:33728
	s_waitcnt vmcnt(27)
	s_waitcnt lgkmcnt(6)
	v_mfma_f32_16x16x32_bf16 v[42:45], v[228:231], v[96:99], v[42:45]
	v_mfma_f32_16x16x32_bf16 v[46:49], v[232:235], v[96:99], v[46:49]
	ds_read_b128 v[228:231], v61 offset:512
	ds_read_b128 v[232:235], v61 offset:33792
	s_waitcnt vmcnt(26)
	s_waitcnt lgkmcnt(6)
	v_mfma_f32_16x16x32_bf16 v[42:45], v[236:239], v[100:103], v[42:45]
	v_mfma_f32_16x16x32_bf16 v[46:49], v[240:243], v[100:103], v[46:49]
	ds_read_b128 v[236:239], v61 offset:576
	ds_read_b128 v[240:243], v61 offset:33856
	s_waitcnt vmcnt(25)
	s_waitcnt lgkmcnt(6)
	v_mfma_f32_16x16x32_bf16 v[42:45], v[244:247], v[104:107], v[42:45]
	v_mfma_f32_16x16x32_bf16 v[46:49], v[248:251], v[104:107], v[46:49]
	ds_read_b128 v[244:247], v61 offset:640
	ds_read_b128 v[248:251], v61 offset:33920
	s_waitcnt vmcnt(24)
	s_waitcnt lgkmcnt(6)
	v_mfma_f32_16x16x32_bf16 v[42:45], v[34:37], v[108:111], v[42:45]
	v_mfma_f32_16x16x32_bf16 v[46:49], v[38:41], v[108:111], v[46:49]
	ds_read_b128 v[34:37], v61 offset:704
	ds_read_b128 v[38:41], v61 offset:33984
	s_waitcnt vmcnt(23)
	s_waitcnt lgkmcnt(6)
	v_mfma_f32_16x16x32_bf16 v[42:45], v[228:231], v[112:115], v[42:45]
	v_mfma_f32_16x16x32_bf16 v[46:49], v[232:235], v[112:115], v[46:49]
	ds_read_b128 v[228:231], v61 offset:768
	ds_read_b128 v[232:235], v61 offset:34048
	s_waitcnt vmcnt(22)
	s_waitcnt lgkmcnt(6)
	v_mfma_f32_16x16x32_bf16 v[42:45], v[236:239], v[116:119], v[42:45]
	v_mfma_f32_16x16x32_bf16 v[46:49], v[240:243], v[116:119], v[46:49]
	ds_read_b128 v[236:239], v61 offset:832
	ds_read_b128 v[240:243], v61 offset:34112
	s_waitcnt vmcnt(21)
	s_waitcnt lgkmcnt(6)
	v_mfma_f32_16x16x32_bf16 v[42:45], v[244:247], v[120:123], v[42:45]
	v_mfma_f32_16x16x32_bf16 v[46:49], v[248:251], v[120:123], v[46:49]
	ds_read_b128 v[244:247], v61 offset:896
	ds_read_b128 v[248:251], v61 offset:34176
	s_waitcnt vmcnt(20)
; __device__ __forceinline__ unsigned cvt_pk_bf16(float lo, float hi) { const f32x2c f = {lo, hi}; return __builtin_bit_cast(unsigned, __builtin_convertvector(f, bf16x2c)); }
;     __device__ __forceinline__ void operator()(const f32x4 (&acc)[2][2][4][2], const Unit& u, int wr, int wc, int fr, int fq) const {
;     ...
;                 for (int bj = 0; bj < 2; ++bj) { const f32x4 v0 = acc[ai][bj][m][0], v1 = acc[ai][bj][m][1];
;                     u32x4 w; w.x = cvt_pk_bf16(v0[0], v0[1]); w.y = cvt_pk_bf16(v0[2], v0[3]); w.z = cvt_pk_bf16(v1[0], v1[1]); w.w = cvt_pk_bf16(v1[2], v1[3]);
;                     *(u32x4*)(rowp + bj * HALF) = w; } }
	s_waitcnt lgkmcnt(6)
	v_mfma_f32_16x16x32_bf16 v[42:45], v[34:37], v[124:127], v[42:45]
	v_mfma_f32_16x16x32_bf16 v[46:49], v[38:41], v[124:127], v[46:49]
	ds_read_b128 v[34:37], v61 offset:960
	ds_read_b128 v[38:41], v61 offset:34240
	s_waitcnt vmcnt(19)
	s_waitcnt lgkmcnt(6)
	v_mfma_f32_16x16x32_bf16 v[42:45], v[228:231], v[128:131], v[42:45]
	v_mfma_f32_16x16x32_bf16 v[46:49], v[232:235], v[128:131], v[46:49]
	ds_read_b128 v[228:231], v61 offset:1024
	ds_read_b128 v[232:235], v61 offset:34304
	s_waitcnt vmcnt(18)
	s_waitcnt lgkmcnt(6)
	v_mfma_f32_16x16x32_bf16 v[42:45], v[236:239], v[132:135], v[42:45]
	v_mfma_f32_16x16x32_bf16 v[46:49], v[240:243], v[132:135], v[46:49]
	ds_read_b128 v[236:239], v61 offset:1088
	ds_read_b128 v[240:243], v61 offset:34368
	s_waitcnt vmcnt(17)
	s_waitcnt lgkmcnt(6)
	v_mfma_f32_16x16x32_bf16 v[42:45], v[244:247], v[136:139], v[42:45]
	v_mfma_f32_16x16x32_bf16 v[46:49], v[248:251], v[136:139], v[46:49]
	ds_read_b128 v[244:247], v61 offset:1152
	ds_read_b128 v[248:251], v61 offset:34432
	s_waitcnt vmcnt(16)
	s_waitcnt lgkmcnt(6)
	v_mfma_f32_16x16x32_bf16 v[42:45], v[34:37], v[140:143], v[42:45]
	v_mfma_f32_16x16x32_bf16 v[46:49], v[38:41], v[140:143], v[46:49]
	ds_read_b128 v[34:37], v61 offset:1216
	ds_read_b128 v[38:41], v61 offset:34496
	s_waitcnt vmcnt(15)
	s_waitcnt lgkmcnt(6)
	v_mfma_f32_16x16x32_bf16 v[42:45], v[228:231], v[144:147], v[42:45]
	v_mfma_f32_16x16x32_bf16 v[46:49], v[232:235], v[144:147], v[46:49]
	ds_read_b128 v[228:231], v61 offset:1280
	ds_read_b128 v[232:235], v61 offset:34560
	s_waitcnt vmcnt(14)
	s_waitcnt lgkmcnt(6)
	v_mfma_f32_16x16x32_bf16 v[42:45], v[236:239], v[148:151], v[42:45]
	v_mfma_f32_16x16x32_bf16 v[46:49], v[240:243], v[148:151], v[46:49]
	ds_read_b128 v[236:239], v61 offset:1344
	ds_read_b128 v[240:243], v61 offset:34624
	s_waitcnt vmcnt(13)
	s_waitcnt lgkmcnt(6)
	v_mfma_f32_16x16x32_bf16 v[42:45], v[244:247], v[156:159], v[42:45]
	v_mfma_f32_16x16x32_bf16 v[46:49], v[248:251], v[156:159], v[46:49]
	ds_read_b128 v[244:247], v61 offset:1408
	ds_read_b128 v[248:251], v61 offset:34688
	s_waitcnt vmcnt(12)
	s_waitcnt lgkmcnt(6)
	v_mfma_f32_16x16x32_bf16 v[42:45], v[34:37], v[160:163], v[42:45]
	v_mfma_f32_16x16x32_bf16 v[46:49], v[38:41], v[160:163], v[46:49]
	ds_read_b128 v[34:37], v61 offset:1472
	ds_read_b128 v[38:41], v61 offset:34752
	s_waitcnt vmcnt(11)
	s_waitcnt lgkmcnt(6)
	v_mfma_f32_16x16x32_bf16 v[42:45], v[228:231], v[164:167], v[42:45]
	v_mfma_f32_16x16x32_bf16 v[46:49], v[232:235], v[164:167], v[46:49]
	ds_read_b128 v[228:231], v61 offset:1536
	ds_read_b128 v[232:235], v61 offset:34816
	s_waitcnt vmcnt(10)
	s_waitcnt lgkmcnt(6)
	v_mfma_f32_16x16x32_bf16 v[42:45], v[236:239], v[168:171], v[42:45]
	v_mfma_f32_16x16x32_bf16 v[46:49], v[240:243], v[168:171], v[46:49]
	ds_read_b128 v[236:239], v61 offset:1600
	ds_read_b128 v[240:243], v61 offset:34880
	s_waitcnt vmcnt(9)
	s_waitcnt lgkmcnt(6)
	v_mfma_f32_16x16x32_bf16 v[42:45], v[244:247], v[172:175], v[42:45]
	v_mfma_f32_16x16x32_bf16 v[46:49], v[248:251], v[172:175], v[46:49]
	ds_read_b128 v[244:247], v61 offset:1664
	ds_read_b128 v[248:251], v61 offset:34944
	s_waitcnt vmcnt(8)
	s_waitcnt lgkmcnt(6)
	v_mfma_f32_16x16x32_bf16 v[42:45], v[34:37], v[176:179], v[42:45]
	v_mfma_f32_16x16x32_bf16 v[46:49], v[38:41], v[176:179], v[46:49]
	ds_read_b128 v[34:37], v61 offset:1728
	ds_read_b128 v[38:41], v61 offset:35008
	s_waitcnt vmcnt(7)
	s_waitcnt lgkmcnt(6)
	v_mfma_f32_16x16x32_bf16 v[42:45], v[228:231], v[180:183], v[42:45]
	v_mfma_f32_16x16x32_bf16 v[46:49], v[232:235], v[180:183], v[46:49]
	ds_read_b128 v[228:231], v61 offset:1792
	ds_read_b128 v[232:235], v61 offset:35072
	s_waitcnt vmcnt(6)
	s_waitcnt lgkmcnt(6)
	v_mfma_f32_16x16x32_bf16 v[42:45], v[236:239], v[184:187], v[42:45]
	v_mfma_f32_16x16x32_bf16 v[46:49], v[240:243], v[184:187], v[46:49]
	ds_read_b128 v[236:239], v61 offset:1856
	ds_read_b128 v[240:243], v61 offset:35136
	s_waitcnt vmcnt(5)
	s_waitcnt lgkmcnt(6)
	v_mfma_f32_16x16x32_bf16 v[42:45], v[244:247], v[188:191], v[42:45]
	v_mfma_f32_16x16x32_bf16 v[46:49], v[248:251], v[188:191], v[46:49]
	ds_read_b128 v[244:247], v61 offset:1920
	ds_read_b128 v[248:251], v61 offset:35200
	s_waitcnt vmcnt(4)
	s_waitcnt lgkmcnt(6)
	v_mfma_f32_16x16x32_bf16 v[42:45], v[34:37], v[192:195], v[42:45]
	v_mfma_f32_16x16x32_bf16 v[46:49], v[38:41], v[192:195], v[46:49]
	ds_read_b128 v[34:37], v61 offset:1984
	ds_read_b128 v[38:41], v61 offset:35264
	s_waitcnt vmcnt(3)
	s_waitcnt lgkmcnt(6)
	v_mfma_f32_16x16x32_bf16 v[42:45], v[228:231], v[196:199], v[42:45]
	v_mfma_f32_16x16x32_bf16 v[46:49], v[232:235], v[196:199], v[46:49]
	s_waitcnt vmcnt(2)
	s_waitcnt lgkmcnt(4)
	v_mfma_f32_16x16x32_bf16 v[42:45], v[236:239], v[200:203], v[42:45]
	v_mfma_f32_16x16x32_bf16 v[46:49], v[240:243], v[200:203], v[46:49]
	s_waitcnt vmcnt(1)
	s_waitcnt lgkmcnt(2)
	v_mfma_f32_16x16x32_bf16 v[42:45], v[244:247], v[204:207], v[42:45]
	v_mfma_f32_16x16x32_bf16 v[46:49], v[248:251], v[204:207], v[46:49]
	s_waitcnt vmcnt(0)
	s_waitcnt lgkmcnt(0)
	v_mfma_f32_16x16x32_bf16 v[42:45], v[34:37], v[224:227], v[42:45]
	v_mfma_f32_16x16x32_bf16 v[46:49], v[38:41], v[224:227], v[46:49]
	s_nop 7
	s_nop 1
	v_cvt_pk_bf16_f32 v64, v42, v43
	v_cvt_pk_bf16_f32 v65, v44, v45
	v_cvt_pk_bf16_f32 v66, v46, v47
	v_cvt_pk_bf16_f32 v67, v48, v49
	global_store_dwordx4 v63, v[64:67], s[68:69]
